# cache policy: nt on the MoE-down output stores (2 rows x 512B pieces, read once by the next phase)
# speedup vs baseline: 1.0335x; 1.0017x over previous
; __device__ __forceinline__ unsigned cvt_pk_bf16(float lo, float hi) { unsigned r; asm("v_cvt_pk_bf16_f32 %0, %1, %2" : "=v"(r) : "v"(lo), "v"(hi)); return r; }
;     __device__ __forceinline__ void operator()(const f32x4 (&acc)[2][2][4][2], const pg8::Unit& u, int wr, int wc, int fr, int fq, LAS unsigned char* lds) const {
;     ...
; #pragma unroll
;         for (int ai = 0; ai < 2; ++ai)
; #pragma unroll
;             for (int m = 0; m < 4; ++m) { const int r = 128 * ai + 64 * wr + 16 * m + fr; if (r >= u.nvalid) continue;
; #pragma unroll
;                 for (int bj = 0; bj < 2; ++bj) { const int col = 256 * u.pn + 128 * bj + 32 * wc + 8 * fq;
;                     const f32x4 v0 = (acc[ai][bj][m][0] * dq + bv[bj][0]) * gw[ai][m], v1 = (acc[ai][bj][m][1] * dq + bv[bj][1]) * gw[ai][m];
;                     u32x4 o; o.x = cvt_pk_bf16(v0.x, v0.y); o.y = cvt_pk_bf16(v0.z, v0.w); o.z = cvt_pk_bf16(v1.x, v1.y); o.w = cvt_pk_bf16(v1.z, v1.w);
;                     *(u32x4*)(YK + (size_t)slot[ai][m] * D + col) = o; } }
.LBB0_2349:
	s_or_b64 exec, exec, s[4:5]
	s_waitcnt lgkmcnt(0)
	s_barrier
	ds_read_b128 v[182:185], v243
	ds_read_b128 v[186:189], v244
	ds_read_b32 v190, v246
	ds_read_b32 v192, v246 offset:8
	s_waitcnt lgkmcnt(0)
	s_barrier
	v_add_u32_e32 v194, 0, v239
	v_cmp_lt_i32_e32 vcc, v194, v207
	s_and_saveexec_b64 s[4:5], vcc
	v_ashrrev_i32_e32 v191, 31, v190
	v_lshlrev_b64 v[190:191], 11, v[190:191]
	v_lshl_add_u64 v[190:191], v[240:241], 0, v[190:191]
	global_store_dwordx4 v[190:191], v[182:185], off nt
	s_or_b64 exec, exec, s[4:5]
	v_add_u32_e32 v194, 2, v239
	v_cmp_lt_i32_e32 vcc, v194, v207
	s_and_saveexec_b64 s[4:5], vcc
	v_ashrrev_i32_e32 v193, 31, v192
	v_lshlrev_b64 v[192:193], 11, v[192:193]
	v_lshl_add_u64 v[192:193], v[240:241], 0, v[192:193]
	global_store_dwordx4 v[192:193], v[186:189], off nt
	s_or_b64 exec, exec, s[4:5]
	v_add_u32_e32 v21, 16, v19
	v_cmp_lt_i32_e32 vcc, v21, v207
	s_and_saveexec_b64 s[4:5], vcc
	s_cbranch_execz .LBB0_2351
	v_mov_b32_e32 v205, v204
	s_waitcnt lgkmcnt(0)
	v_pk_fma_f32 v[36:37], v[204:205], v[180:181], v[16:17]
	v_pk_fma_f32 v[38:39], v[208:209], v[178:179], v[14:15]
	v_pk_mul_f32 v[40:41], v[34:35], v[36:37] op_sel_hi:[0,1]
	v_pk_mul_f32 v[36:37], v[34:35], v[38:39] op_sel_hi:[0,1]
	v_cvt_pk_bf16_f32 v36, v36, v37
	v_cvt_pk_bf16_f32 v37, v40, v41
	v_ashrrev_i32_e32 v41, 31, v32
	v_mov_b32_e32 v40, v32
	v_pk_fma_f32 v[38:39], v[204:205], v[176:177], v[12:13]
	v_pk_fma_f32 v[42:43], v[208:209], v[174:175], v[10:11]
	v_lshlrev_b64 v[40:41], 11, v[40:41]
	v_pk_mul_f32 v[44:45], v[34:35], v[38:39] op_sel_hi:[0,1]
	v_pk_mul_f32 v[38:39], v[34:35], v[42:43] op_sel_hi:[0,1]
	v_lshl_add_u64 v[40:41], s[42:43], 0, v[40:41]
	v_cvt_pk_bf16_f32 v38, v38, v39
	v_cvt_pk_bf16_f32 v39, v44, v45
	v_lshl_add_u64 v[40:41], v[22:23], 1, v[40:41]
	ds_write_b128 v245, v[36:39]
	v_pk_fma_f32 v[44:45], v[208:209], v[166:167], v[2:3]
	s_nop 0
	v_pk_fma_f32 v[36:37], v[204:205], v[172:173], v[8:9]
	v_pk_fma_f32 v[38:39], v[208:209], v[170:171], v[6:7]
	v_pk_mul_f32 v[42:43], v[34:35], v[36:37] op_sel_hi:[0,1]
	v_pk_mul_f32 v[36:37], v[34:35], v[38:39] op_sel_hi:[0,1]
	v_pk_fma_f32 v[38:39], v[204:205], v[168:169], v[4:5]
	v_cvt_pk_bf16_f32 v36, v36, v37
	v_cvt_pk_bf16_f32 v37, v42, v43
	s_nop 0
	v_pk_mul_f32 v[46:47], v[34:35], v[38:39] op_sel_hi:[0,1]
	v_pk_mul_f32 v[38:39], v[34:35], v[44:45] op_sel_hi:[0,1]
	v_cvt_pk_bf16_f32 v38, v38, v39
	v_cvt_pk_bf16_f32 v39, v46, v47
	ds_write_b128 v245, v[36:39] offset:256
.LBB0_2351:
	s_or_b64 exec, exec, s[4:5]
	s_waitcnt lgkmcnt(0)
	s_barrier
	ds_read_b128 v[182:185], v243
	ds_read_b128 v[186:189], v244
	ds_read_b32 v190, v246 offset:64
	ds_read_b32 v192, v246 offset:72
	s_waitcnt lgkmcnt(0)
	s_barrier
	v_add_u32_e32 v194, 16, v239
	v_cmp_lt_i32_e32 vcc, v194, v207
	s_and_saveexec_b64 s[4:5], vcc
	v_ashrrev_i32_e32 v191, 31, v190
	v_lshlrev_b64 v[190:191], 11, v[190:191]
	v_lshl_add_u64 v[190:191], v[240:241], 0, v[190:191]
	global_store_dwordx4 v[190:191], v[182:185], off nt
	s_or_b64 exec, exec, s[4:5]
	v_add_u32_e32 v194, 18, v239
	v_cmp_lt_i32_e32 vcc, v194, v207
	s_and_saveexec_b64 s[4:5], vcc
	v_ashrrev_i32_e32 v193, 31, v192
	v_lshlrev_b64 v[192:193], 11, v[192:193]
	v_lshl_add_u64 v[192:193], v[240:241], 0, v[192:193]
	global_store_dwordx4 v[192:193], v[186:189], off nt
	s_or_b64 exec, exec, s[4:5]
	v_add_u32_e32 v21, 32, v19
	v_cmp_lt_i32_e32 vcc, v21, v207
	s_and_saveexec_b64 s[4:5], vcc
	s_cbranch_execz .LBB0_2353
	v_mov_b32_e32 v205, v204
	s_waitcnt lgkmcnt(0)
	v_pk_fma_f32 v[38:39], v[208:209], v[162:163], v[14:15]
	v_mov_b32_e32 v32, v35
	v_pk_fma_f32 v[36:37], v[204:205], v[164:165], v[16:17]
	v_pk_mul_f32 v[34:35], v[32:33], v[38:39] op_sel_hi:[0,1]
	v_pk_fma_f32 v[38:39], v[204:205], v[160:161], v[12:13]
	v_pk_mul_f32 v[36:37], v[32:33], v[36:37] op_sel_hi:[0,1]
	v_pk_mul_f32 v[38:39], v[32:33], v[38:39] op_sel_hi:[0,1]
	v_cvt_pk_bf16_f32 v34, v34, v35
	v_cvt_pk_bf16_f32 v35, v36, v37
	v_cvt_pk_bf16_f32 v37, v38, v39
	v_ashrrev_i32_e32 v39, 31, v33
	v_mov_b32_e32 v38, v33
	v_lshlrev_b64 v[38:39], 11, v[38:39]
	v_lshl_add_u64 v[38:39], s[42:43], 0, v[38:39]
	v_pk_fma_f32 v[40:41], v[208:209], v[158:159], v[10:11]
	v_lshl_add_u64 v[38:39], v[22:23], 1, v[38:39]
	v_pk_mul_f32 v[40:41], v[32:33], v[40:41] op_sel_hi:[0,1]
	v_cvt_pk_bf16_f32 v36, v40, v41
	ds_write_b128 v245, v[34:37]
	v_pk_fma_f32 v[40:41], v[204:205], v[152:153], v[4:5]
	v_pk_fma_f32 v[42:43], v[208:209], v[150:151], v[2:3]
	v_pk_fma_f32 v[34:35], v[204:205], v[156:157], v[8:9]
	v_pk_fma_f32 v[36:37], v[208:209], v[154:155], v[6:7]
	v_pk_mul_f32 v[34:35], v[32:33], v[34:35] op_sel_hi:[0,1]
	v_pk_mul_f32 v[36:37], v[32:33], v[36:37] op_sel_hi:[0,1]
	v_pk_mul_f32 v[40:41], v[32:33], v[40:41] op_sel_hi:[0,1]
	v_pk_mul_f32 v[42:43], v[32:33], v[42:43] op_sel_hi:[0,1]
	v_cvt_pk_bf16_f32 v32, v36, v37
	v_cvt_pk_bf16_f32 v33, v34, v35
	v_cvt_pk_bf16_f32 v34, v42, v43
	v_cvt_pk_bf16_f32 v35, v40, v41
	ds_write_b128 v245, v[32:35] offset:256
; __device__ __forceinline__ unsigned cvt_pk_bf16(float lo, float hi) { unsigned r; asm("v_cvt_pk_bf16_f32 %0, %1, %2" : "=v"(r) : "v"(lo), "v"(hi)); return r; }
;     __device__ __forceinline__ void operator()(const f32x4 (&acc)[2][2][4][2], const pg8::Unit& u, int wr, int wc, int fr, int fq, LAS unsigned char* lds) const {
;     ...
; #pragma unroll
;         for (int ai = 0; ai < 2; ++ai)
; #pragma unroll
;             for (int m = 0; m < 4; ++m) { const int r = 128 * ai + 64 * wr + 16 * m + fr; if (r >= u.nvalid) continue;
; #pragma unroll
;                 for (int bj = 0; bj < 2; ++bj) { const int col = 256 * u.pn + 128 * bj + 32 * wc + 8 * fq;
;                     const f32x4 v0 = (acc[ai][bj][m][0] * dq + bv[bj][0]) * gw[ai][m], v1 = (acc[ai][bj][m][1] * dq + bv[bj][1]) * gw[ai][m];
;                     u32x4 o; o.x = cvt_pk_bf16(v0.x, v0.y); o.y = cvt_pk_bf16(v0.z, v0.w); o.z = cvt_pk_bf16(v1.x, v1.y); o.w = cvt_pk_bf16(v1.z, v1.w);
;                     *(u32x4*)(YK + (size_t)slot[ai][m] * D + col) = o; } }
.LBB0_2353:
	s_or_b64 exec, exec, s[4:5]
	s_waitcnt lgkmcnt(0)
	s_barrier
	ds_read_b128 v[182:185], v243
	ds_read_b128 v[186:189], v244
	ds_read_b32 v190, v246 offset:128
	ds_read_b32 v192, v246 offset:136
	s_waitcnt lgkmcnt(0)
	s_barrier
	v_add_u32_e32 v194, 32, v239
	v_cmp_lt_i32_e32 vcc, v194, v207
	s_and_saveexec_b64 s[4:5], vcc
	v_ashrrev_i32_e32 v191, 31, v190
	v_lshlrev_b64 v[190:191], 11, v[190:191]
	v_lshl_add_u64 v[190:191], v[240:241], 0, v[190:191]
	global_store_dwordx4 v[190:191], v[182:185], off nt
	s_or_b64 exec, exec, s[4:5]
	v_add_u32_e32 v194, 34, v239
	v_cmp_lt_i32_e32 vcc, v194, v207
	s_and_saveexec_b64 s[4:5], vcc
	v_ashrrev_i32_e32 v193, 31, v192
	v_lshlrev_b64 v[192:193], 11, v[192:193]
	v_lshl_add_u64 v[192:193], v[240:241], 0, v[192:193]
	global_store_dwordx4 v[192:193], v[186:189], off nt
	s_or_b64 exec, exec, s[4:5]
	v_add_u32_e32 v21, 48, v19
	v_cmp_lt_i32_e32 vcc, v21, v207
	s_and_saveexec_b64 s[4:5], vcc
	s_cbranch_execz .LBB0_2355
	v_mov_b32_e32 v205, v204
	s_waitcnt lgkmcnt(0)
	v_pk_fma_f32 v[32:33], v[204:205], v[148:149], v[16:17]
	v_pk_fma_f32 v[34:35], v[208:209], v[146:147], v[14:15]
	v_pk_mul_f32 v[36:37], v[30:31], v[32:33] op_sel_hi:[0,1]
	v_pk_mul_f32 v[32:33], v[30:31], v[34:35] op_sel_hi:[0,1]
	v_cvt_pk_bf16_f32 v32, v32, v33
	v_cvt_pk_bf16_f32 v33, v36, v37
	v_ashrrev_i32_e32 v37, 31, v28
	v_mov_b32_e32 v36, v28
	v_pk_fma_f32 v[34:35], v[204:205], v[144:145], v[12:13]
	v_pk_fma_f32 v[38:39], v[208:209], v[142:143], v[10:11]
	v_lshlrev_b64 v[36:37], 11, v[36:37]
	v_pk_mul_f32 v[40:41], v[30:31], v[34:35] op_sel_hi:[0,1]
	v_pk_mul_f32 v[34:35], v[30:31], v[38:39] op_sel_hi:[0,1]
	v_lshl_add_u64 v[36:37], s[42:43], 0, v[36:37]
	v_cvt_pk_bf16_f32 v34, v34, v35
	v_cvt_pk_bf16_f32 v35, v40, v41
	v_lshl_add_u64 v[36:37], v[22:23], 1, v[36:37]
	ds_write_b128 v245, v[32:35]
	v_pk_fma_f32 v[40:41], v[208:209], v[134:135], v[2:3]
	s_nop 0
	v_pk_fma_f32 v[32:33], v[204:205], v[140:141], v[8:9]
	v_pk_fma_f32 v[34:35], v[208:209], v[138:139], v[6:7]
	v_pk_mul_f32 v[38:39], v[30:31], v[32:33] op_sel_hi:[0,1]
	v_pk_mul_f32 v[32:33], v[30:31], v[34:35] op_sel_hi:[0,1]
	v_pk_fma_f32 v[34:35], v[204:205], v[136:137], v[4:5]
	v_cvt_pk_bf16_f32 v32, v32, v33
	v_cvt_pk_bf16_f32 v33, v38, v39
	s_nop 0
	v_pk_mul_f32 v[42:43], v[30:31], v[34:35] op_sel_hi:[0,1]
	v_pk_mul_f32 v[34:35], v[30:31], v[40:41] op_sel_hi:[0,1]
	v_cvt_pk_bf16_f32 v34, v34, v35
	v_cvt_pk_bf16_f32 v35, v42, v43
	ds_write_b128 v245, v[32:35] offset:256
.LBB0_2355:
	s_or_b64 exec, exec, s[4:5]
	s_waitcnt lgkmcnt(0)
	s_barrier
	ds_read_b128 v[182:185], v243
	ds_read_b128 v[186:189], v244
	ds_read_b32 v190, v246 offset:192
	ds_read_b32 v192, v246 offset:200
	s_waitcnt lgkmcnt(0)
	s_barrier
	v_add_u32_e32 v194, 48, v239
	v_cmp_lt_i32_e32 vcc, v194, v207
	s_and_saveexec_b64 s[4:5], vcc
	v_ashrrev_i32_e32 v191, 31, v190
	v_lshlrev_b64 v[190:191], 11, v[190:191]
	v_lshl_add_u64 v[190:191], v[240:241], 0, v[190:191]
	global_store_dwordx4 v[190:191], v[182:185], off nt
	s_or_b64 exec, exec, s[4:5]
	v_add_u32_e32 v194, 50, v239
	v_cmp_lt_i32_e32 vcc, v194, v207
	s_and_saveexec_b64 s[4:5], vcc
	v_ashrrev_i32_e32 v193, 31, v192
	v_lshlrev_b64 v[192:193], 11, v[192:193]
	v_lshl_add_u64 v[192:193], v[240:241], 0, v[192:193]
	global_store_dwordx4 v[192:193], v[186:189], off nt
	s_or_b64 exec, exec, s[4:5]
	v_add_u32_e32 v21, 0x80, v19
	v_cmp_lt_i32_e32 vcc, v21, v207
	s_and_saveexec_b64 s[4:5], vcc
	s_cbranch_execz .LBB0_2357
	v_mov_b32_e32 v205, v204
	s_waitcnt lgkmcnt(0)
	v_pk_fma_f32 v[34:35], v[208:209], v[130:131], v[14:15]
	v_mov_b32_e32 v28, v31
	v_pk_fma_f32 v[32:33], v[204:205], v[132:133], v[16:17]
	v_pk_mul_f32 v[30:31], v[28:29], v[34:35] op_sel_hi:[0,1]
	v_pk_fma_f32 v[34:35], v[204:205], v[128:129], v[12:13]
	v_pk_mul_f32 v[32:33], v[28:29], v[32:33] op_sel_hi:[0,1]
	v_pk_mul_f32 v[34:35], v[28:29], v[34:35] op_sel_hi:[0,1]
	v_cvt_pk_bf16_f32 v30, v30, v31
	v_cvt_pk_bf16_f32 v31, v32, v33
	v_cvt_pk_bf16_f32 v33, v34, v35
	v_ashrrev_i32_e32 v35, 31, v29
	v_mov_b32_e32 v34, v29
	v_lshlrev_b64 v[34:35], 11, v[34:35]
	v_lshl_add_u64 v[34:35], s[42:43], 0, v[34:35]
	v_pk_fma_f32 v[36:37], v[208:209], v[126:127], v[10:11]
	v_lshl_add_u64 v[34:35], v[22:23], 1, v[34:35]
	v_pk_mul_f32 v[36:37], v[28:29], v[36:37] op_sel_hi:[0,1]
	v_cvt_pk_bf16_f32 v32, v36, v37
	ds_write_b128 v245, v[30:33]
	v_pk_fma_f32 v[36:37], v[204:205], v[120:121], v[4:5]
	v_pk_fma_f32 v[38:39], v[208:209], v[118:119], v[2:3]
	v_pk_fma_f32 v[30:31], v[204:205], v[124:125], v[8:9]
	v_pk_fma_f32 v[32:33], v[208:209], v[122:123], v[6:7]
	v_pk_mul_f32 v[30:31], v[28:29], v[30:31] op_sel_hi:[0,1]
	v_pk_mul_f32 v[32:33], v[28:29], v[32:33] op_sel_hi:[0,1]
	v_pk_mul_f32 v[36:37], v[28:29], v[36:37] op_sel_hi:[0,1]
	v_pk_mul_f32 v[38:39], v[28:29], v[38:39] op_sel_hi:[0,1]
	v_cvt_pk_bf16_f32 v28, v32, v33
	v_cvt_pk_bf16_f32 v29, v30, v31
	v_cvt_pk_bf16_f32 v30, v38, v39
	v_cvt_pk_bf16_f32 v31, v36, v37
	ds_write_b128 v245, v[28:31] offset:256
; __device__ __forceinline__ unsigned cvt_pk_bf16(float lo, float hi) { unsigned r; asm("v_cvt_pk_bf16_f32 %0, %1, %2" : "=v"(r) : "v"(lo), "v"(hi)); return r; }
;     __device__ __forceinline__ void operator()(const f32x4 (&acc)[2][2][4][2], const pg8::Unit& u, int wr, int wc, int fr, int fq, LAS unsigned char* lds) const {
;     ...
; #pragma unroll
;         for (int ai = 0; ai < 2; ++ai)
; #pragma unroll
;             for (int m = 0; m < 4; ++m) { const int r = 128 * ai + 64 * wr + 16 * m + fr; if (r >= u.nvalid) continue;
; #pragma unroll
;                 for (int bj = 0; bj < 2; ++bj) { const int col = 256 * u.pn + 128 * bj + 32 * wc + 8 * fq;
;                     const f32x4 v0 = (acc[ai][bj][m][0] * dq + bv[bj][0]) * gw[ai][m], v1 = (acc[ai][bj][m][1] * dq + bv[bj][1]) * gw[ai][m];
;                     u32x4 o; o.x = cvt_pk_bf16(v0.x, v0.y); o.y = cvt_pk_bf16(v0.z, v0.w); o.z = cvt_pk_bf16(v1.x, v1.y); o.w = cvt_pk_bf16(v1.z, v1.w);
;                     *(u32x4*)(YK + (size_t)slot[ai][m] * D + col) = o; } }
.LBB0_2357:
	s_or_b64 exec, exec, s[4:5]
	s_waitcnt lgkmcnt(0)
	s_barrier
	ds_read_b128 v[182:185], v243
	ds_read_b128 v[186:189], v244
	ds_read_b32 v190, v246 offset:512
	ds_read_b32 v192, v246 offset:520
	s_waitcnt lgkmcnt(0)
	s_barrier
	v_add_u32_e32 v194, 0x80, v239
	v_cmp_lt_i32_e32 vcc, v194, v207
	s_and_saveexec_b64 s[4:5], vcc
	v_ashrrev_i32_e32 v191, 31, v190
	v_lshlrev_b64 v[190:191], 11, v[190:191]
	v_lshl_add_u64 v[190:191], v[240:241], 0, v[190:191]
	global_store_dwordx4 v[190:191], v[182:185], off nt
	s_or_b64 exec, exec, s[4:5]
	v_add_u32_e32 v194, 0x82, v239
	v_cmp_lt_i32_e32 vcc, v194, v207
	s_and_saveexec_b64 s[4:5], vcc
	v_ashrrev_i32_e32 v193, 31, v192
	v_lshlrev_b64 v[192:193], 11, v[192:193]
	v_lshl_add_u64 v[192:193], v[240:241], 0, v[192:193]
	global_store_dwordx4 v[192:193], v[186:189], off nt
	s_or_b64 exec, exec, s[4:5]
	v_add_u32_e32 v21, 0x90, v19
	v_cmp_lt_i32_e32 vcc, v21, v207
	s_and_saveexec_b64 s[4:5], vcc
	s_cbranch_execz .LBB0_2359
	v_mov_b32_e32 v205, v204
	s_waitcnt lgkmcnt(0)
	v_pk_fma_f32 v[28:29], v[204:205], v[116:117], v[16:17]
	v_pk_fma_f32 v[30:31], v[208:209], v[114:115], v[14:15]
	v_pk_mul_f32 v[32:33], v[26:27], v[28:29] op_sel_hi:[0,1]
	v_pk_mul_f32 v[28:29], v[26:27], v[30:31] op_sel_hi:[0,1]
	v_cvt_pk_bf16_f32 v28, v28, v29
	v_cvt_pk_bf16_f32 v29, v32, v33
	v_ashrrev_i32_e32 v33, 31, v24
	v_mov_b32_e32 v32, v24
	v_pk_fma_f32 v[30:31], v[204:205], v[112:113], v[12:13]
	v_pk_fma_f32 v[34:35], v[208:209], v[110:111], v[10:11]
	v_lshlrev_b64 v[32:33], 11, v[32:33]
	v_pk_mul_f32 v[36:37], v[26:27], v[30:31] op_sel_hi:[0,1]
	v_pk_mul_f32 v[30:31], v[26:27], v[34:35] op_sel_hi:[0,1]
	v_lshl_add_u64 v[32:33], s[42:43], 0, v[32:33]
	v_cvt_pk_bf16_f32 v30, v30, v31
	v_cvt_pk_bf16_f32 v31, v36, v37
	v_lshl_add_u64 v[32:33], v[22:23], 1, v[32:33]
	ds_write_b128 v245, v[28:31]
	v_pk_fma_f32 v[36:37], v[208:209], v[102:103], v[2:3]
	s_nop 0
	v_pk_fma_f32 v[28:29], v[204:205], v[108:109], v[8:9]
	v_pk_fma_f32 v[30:31], v[208:209], v[106:107], v[6:7]
	v_pk_mul_f32 v[34:35], v[26:27], v[28:29] op_sel_hi:[0,1]
	v_pk_mul_f32 v[28:29], v[26:27], v[30:31] op_sel_hi:[0,1]
	v_pk_fma_f32 v[30:31], v[204:205], v[104:105], v[4:5]
	v_cvt_pk_bf16_f32 v28, v28, v29
	v_cvt_pk_bf16_f32 v29, v34, v35
	s_nop 0
	v_pk_mul_f32 v[38:39], v[26:27], v[30:31] op_sel_hi:[0,1]
	v_pk_mul_f32 v[30:31], v[26:27], v[36:37] op_sel_hi:[0,1]
	v_cvt_pk_bf16_f32 v30, v30, v31
	v_cvt_pk_bf16_f32 v31, v38, v39
	ds_write_b128 v245, v[28:31] offset:256
.LBB0_2359:
	s_or_b64 exec, exec, s[4:5]
	s_waitcnt lgkmcnt(0)
	s_barrier
	ds_read_b128 v[182:185], v243
	ds_read_b128 v[186:189], v244
	ds_read_b32 v190, v246 offset:576
	ds_read_b32 v192, v246 offset:584
	s_waitcnt lgkmcnt(0)
	s_barrier
	v_add_u32_e32 v194, 0x90, v239
	v_cmp_lt_i32_e32 vcc, v194, v207
	s_and_saveexec_b64 s[4:5], vcc
	v_ashrrev_i32_e32 v191, 31, v190
	v_lshlrev_b64 v[190:191], 11, v[190:191]
	v_lshl_add_u64 v[190:191], v[240:241], 0, v[190:191]
	global_store_dwordx4 v[190:191], v[182:185], off nt
	s_or_b64 exec, exec, s[4:5]
	v_add_u32_e32 v194, 0x92, v239
	v_cmp_lt_i32_e32 vcc, v194, v207
	s_and_saveexec_b64 s[4:5], vcc
	v_ashrrev_i32_e32 v193, 31, v192
	v_lshlrev_b64 v[192:193], 11, v[192:193]
	v_lshl_add_u64 v[192:193], v[240:241], 0, v[192:193]
	global_store_dwordx4 v[192:193], v[186:189], off nt
	s_or_b64 exec, exec, s[4:5]
	v_add_u32_e32 v21, 0xa0, v19
	v_cmp_lt_i32_e32 vcc, v21, v207
	s_and_saveexec_b64 s[4:5], vcc
	s_cbranch_execz .LBB0_2361
	v_mov_b32_e32 v205, v204
	s_waitcnt lgkmcnt(0)
	v_pk_fma_f32 v[30:31], v[208:209], v[98:99], v[14:15]
	v_mov_b32_e32 v24, v27
	v_pk_fma_f32 v[28:29], v[204:205], v[100:101], v[16:17]
	v_pk_mul_f32 v[26:27], v[24:25], v[30:31] op_sel_hi:[0,1]
	v_pk_fma_f32 v[30:31], v[204:205], v[96:97], v[12:13]
	v_pk_mul_f32 v[28:29], v[24:25], v[28:29] op_sel_hi:[0,1]
	v_pk_mul_f32 v[30:31], v[24:25], v[30:31] op_sel_hi:[0,1]
	v_cvt_pk_bf16_f32 v26, v26, v27
	v_cvt_pk_bf16_f32 v27, v28, v29
	v_cvt_pk_bf16_f32 v29, v30, v31
	v_ashrrev_i32_e32 v31, 31, v25
	v_mov_b32_e32 v30, v25
	v_lshlrev_b64 v[30:31], 11, v[30:31]
	v_lshl_add_u64 v[30:31], s[42:43], 0, v[30:31]
	v_pk_fma_f32 v[32:33], v[208:209], v[94:95], v[10:11]
	v_lshl_add_u64 v[30:31], v[22:23], 1, v[30:31]
	v_pk_mul_f32 v[32:33], v[24:25], v[32:33] op_sel_hi:[0,1]
	v_cvt_pk_bf16_f32 v28, v32, v33
	ds_write_b128 v245, v[26:29]
	v_pk_fma_f32 v[32:33], v[204:205], v[88:89], v[4:5]
	v_pk_fma_f32 v[34:35], v[208:209], v[86:87], v[2:3]
	v_pk_fma_f32 v[26:27], v[204:205], v[92:93], v[8:9]
	v_pk_fma_f32 v[28:29], v[208:209], v[90:91], v[6:7]
	v_pk_mul_f32 v[26:27], v[24:25], v[26:27] op_sel_hi:[0,1]
	v_pk_mul_f32 v[28:29], v[24:25], v[28:29] op_sel_hi:[0,1]
	v_pk_mul_f32 v[32:33], v[24:25], v[32:33] op_sel_hi:[0,1]
	v_pk_mul_f32 v[34:35], v[24:25], v[34:35] op_sel_hi:[0,1]
	v_cvt_pk_bf16_f32 v24, v28, v29
	v_cvt_pk_bf16_f32 v25, v26, v27
	v_cvt_pk_bf16_f32 v26, v34, v35
	v_cvt_pk_bf16_f32 v27, v32, v33
	ds_write_b128 v245, v[24:27] offset:256
; __device__ __forceinline__ unsigned cvt_pk_bf16(float lo, float hi) { unsigned r; asm("v_cvt_pk_bf16_f32 %0, %1, %2" : "=v"(r) : "v"(lo), "v"(hi)); return r; }
; #define PG8_BAR __builtin_amdgcn_s_barrier()
; template <bool FP8, class Epi, class Sched, class ARow, class BBase>
; __device__ __forceinline__ void gemm_phase(LAS unsigned char* lds, const void* Abase, const ARow& AR, const BBase& BB, const Sched& S, const Epi& E, int tid) {
;     ...
;         if (!has_next) break;
; #pragma unroll
;         for (int a = 0; a < 2; ++a)
; #pragma unroll
;             for (int b = 0; b < 2; ++b)
; #pragma unroll
;                 for (int m = 0; m < 4; ++m)
; #pragma unroll
;                     for (int n = 0; n < 2; ++n) acc[a][b][m][n] = (f32x4){0.f, 0.f, 0.f, 0.f};
;         cur = nxt; cB = nB; ++ui;
;         if (wr == 1) PG8_BAR;
;     __device__ __forceinline__ void operator()(const f32x4 (&acc)[2][2][4][2], const pg8::Unit& u, int wr, int wc, int fr, int fq, LAS unsigned char* lds) const {
;     ...
; #pragma unroll
;         for (int ai = 0; ai < 2; ++ai)
; #pragma unroll
;             for (int m = 0; m < 4; ++m) { const int r = 128 * ai + 64 * wr + 16 * m + fr; if (r >= u.nvalid) continue;
; #pragma unroll
;                 for (int bj = 0; bj < 2; ++bj) { const int col = 256 * u.pn + 128 * bj + 32 * wc + 8 * fq;
;                     const f32x4 v0 = (acc[ai][bj][m][0] * dq + bv[bj][0]) * gw[ai][m], v1 = (acc[ai][bj][m][1] * dq + bv[bj][1]) * gw[ai][m];
;                     u32x4 o; o.x = cvt_pk_bf16(v0.x, v0.y); o.y = cvt_pk_bf16(v0.z, v0.w); o.z = cvt_pk_bf16(v1.x, v1.y); o.w = cvt_pk_bf16(v1.z, v1.w);
;                     *(u32x4*)(YK + (size_t)slot[ai][m] * D + col) = o; } }
.LBB0_2361:
	s_or_b64 exec, exec, s[4:5]
	s_waitcnt lgkmcnt(0)
	s_barrier
	ds_read_b128 v[182:185], v243
	ds_read_b128 v[186:189], v244
	ds_read_b32 v190, v246 offset:640
	ds_read_b32 v192, v246 offset:648
	s_waitcnt lgkmcnt(0)
	s_barrier
	v_add_u32_e32 v194, 0xa0, v239
	v_cmp_lt_i32_e32 vcc, v194, v207
	s_and_saveexec_b64 s[4:5], vcc
	v_ashrrev_i32_e32 v191, 31, v190
	v_lshlrev_b64 v[190:191], 11, v[190:191]
	v_lshl_add_u64 v[190:191], v[240:241], 0, v[190:191]
	global_store_dwordx4 v[190:191], v[182:185], off nt
	s_or_b64 exec, exec, s[4:5]
	v_add_u32_e32 v194, 0xa2, v239
	v_cmp_lt_i32_e32 vcc, v194, v207
	s_and_saveexec_b64 s[4:5], vcc
	v_ashrrev_i32_e32 v193, 31, v192
	v_lshlrev_b64 v[192:193], 11, v[192:193]
	v_lshl_add_u64 v[192:193], v[240:241], 0, v[192:193]
	global_store_dwordx4 v[192:193], v[186:189], off nt
	s_or_b64 exec, exec, s[4:5]
	v_add_u32_e32 v19, 0xb0, v19
	v_cmp_lt_i32_e32 vcc, v19, v207
	s_and_saveexec_b64 s[4:5], vcc
	s_cbranch_execz .LBB0_2363
	v_mov_b32_e32 v205, v204
	s_waitcnt lgkmcnt(0)
	v_pk_fma_f32 v[14:15], v[208:209], v[82:83], v[14:15]
	v_pk_fma_f32 v[12:13], v[204:205], v[80:81], v[12:13]
	v_pk_mul_f32 v[14:15], v[18:19], v[14:15] op_sel_hi:[0,1]
	v_pk_fma_f32 v[10:11], v[208:209], v[78:79], v[10:11]
	v_ashrrev_i32_e32 v21, 31, v20
	v_pk_mul_f32 v[24:25], v[18:19], v[12:13] op_sel_hi:[0,1]
	v_pk_mul_f32 v[12:13], v[18:19], v[10:11] op_sel_hi:[0,1]
	v_cvt_pk_bf16_f32 v10, v14, v15
	v_lshlrev_b64 v[14:15], 11, v[20:21]
	v_pk_fma_f32 v[16:17], v[204:205], v[84:85], v[16:17]
	v_lshl_add_u64 v[14:15], s[42:43], 0, v[14:15]
	v_pk_mul_f32 v[16:17], v[18:19], v[16:17] op_sel_hi:[0,1]
	v_cvt_pk_bf16_f32 v11, v16, v17
	v_lshl_add_u64 v[14:15], v[22:23], 1, v[14:15]
	v_pk_fma_f32 v[4:5], v[204:205], v[72:73], v[4:5]
	v_pk_fma_f32 v[2:3], v[208:209], v[70:71], v[2:3]
	v_cvt_pk_bf16_f32 v12, v12, v13
	v_cvt_pk_bf16_f32 v13, v24, v25
	ds_write_b128 v245, v[10:13]
	v_pk_fma_f32 v[8:9], v[204:205], v[76:77], v[8:9]
	v_pk_fma_f32 v[6:7], v[208:209], v[74:75], v[6:7]
	v_pk_mul_f32 v[10:11], v[18:19], v[4:5] op_sel_hi:[0,1]
	v_pk_mul_f32 v[4:5], v[18:19], v[2:3] op_sel_hi:[0,1]
	v_pk_mul_f32 v[8:9], v[18:19], v[8:9] op_sel_hi:[0,1]
	v_pk_mul_f32 v[6:7], v[18:19], v[6:7] op_sel_hi:[0,1]
	v_cvt_pk_bf16_f32 v2, v6, v7
	v_cvt_pk_bf16_f32 v3, v8, v9
	v_cvt_pk_bf16_f32 v4, v4, v5
	v_cvt_pk_bf16_f32 v5, v10, v11
	ds_write_b128 v245, v[2:5] offset:256
.LBB0_2363:
	s_or_b64 exec, exec, s[4:5]
	s_waitcnt lgkmcnt(0)
	s_barrier
	ds_read_b128 v[182:185], v243
	ds_read_b128 v[186:189], v244
	ds_read_b32 v190, v246 offset:704
	ds_read_b32 v192, v246 offset:712
	s_waitcnt lgkmcnt(0)
	s_barrier
	v_add_u32_e32 v194, 0xb0, v239
	v_cmp_lt_i32_e32 vcc, v194, v207
	s_and_saveexec_b64 s[4:5], vcc
	v_ashrrev_i32_e32 v191, 31, v190
	v_lshlrev_b64 v[190:191], 11, v[190:191]
	v_lshl_add_u64 v[190:191], v[240:241], 0, v[190:191]
	global_store_dwordx4 v[190:191], v[182:185], off nt
	s_or_b64 exec, exec, s[4:5]
	v_add_u32_e32 v194, 0xb2, v239
	v_cmp_lt_i32_e32 vcc, v194, v207
	s_and_saveexec_b64 s[4:5], vcc
	v_ashrrev_i32_e32 v193, 31, v192
	v_lshlrev_b64 v[192:193], 11, v[192:193]
	v_lshl_add_u64 v[192:193], v[240:241], 0, v[192:193]
	global_store_dwordx4 v[192:193], v[186:189], off nt
	s_or_b64 exec, exec, s[4:5]
	s_and_b64 vcc, exec, s[0:1]
	s_mov_b64 s[0:1], -1
	s_cbranch_vccnz .LBB0_2325
	s_andn2_b64 vcc, exec, s[28:29]
	s_cbranch_vccnz .LBB0_2324
	s_barrier
	s_branch .LBB0_2324
